# first K iteration peeled with SrcC=0 in the three MF=3 GEMM loops too (cin, qkv, resid), accumulator v_mov zeroing removed
# speedup vs baseline: 1.0032x; 1.0032x over previous
.LBB0_383:
	s_ashr_i32 s49, s48, 31
	s_lshl_b64 s[52:53], s[48:49], 19
	s_add_u32 s52, s10, s52
	s_addc_u32 s53, s11, s53
	s_and_b64 s[42:43], s[42:43], exec
	s_cselect_b32 s49, s53, s55
	s_cselect_b32 s66, s52, s54
	s_add_u32 s42, s56, 0x30080
	s_addc_u32 s43, s57, 0
	s_add_u32 s67, s54, 0x100
	s_addc_u32 s68, s55, 0
	s_mov_b32 s69, -2
	v_add_u32_e32 v96, 0x10000, v157
	ds_read_b128 v[160:163], v96
	ds_read_b128 v[164:167], v96 offset:1024
	ds_read_b128 v[168:171], v96 offset:2048
	ds_read_b128 v[172:175], v96 offset:3072
	s_add_u32 s54, s42, 0xfffd0080
	s_addc_u32 s55, s43, -1
	s_add_i32 s70, 0, 0x10000
	v_add_u32_e32 v96, s70, v157
	s_cmp_eq_u32 s69, 12
	s_cselect_b32 s57, s51, s55
	s_cselect_b32 s56, s50, s54
	s_cselect_b32 s55, s49, s68
	s_cselect_b32 s54, s66, s67
	s_add_i32 m0, s28, 0xc000
	ds_read_b128 v[182:185], v159
	ds_read_b128 v[186:189], v159 offset:1024
	ds_read_b128 v[190:193], v159 offset:2048
	ds_read_b128 v[194:197], v159 offset:3072
	ds_read_b128 v[198:201], v159 offset:4096
	ds_read_b128 v[224:227], v159 offset:5120
	global_load_lds_dwordx4 v150, s[42:43]
	s_add_i32 m0, s28, 0xe000
	s_mov_b64 exec, s[98:99]
	global_load_lds_dwordx4 v152, s[42:43]
	s_mov_b64 exec, -1
	s_setprio 1
	s_barrier
	s_waitcnt lgkmcnt(0)
	v_mfma_f32_16x16x32_bf16 v[134:137], v[160:163], v[182:185], 0
	v_mfma_f32_16x16x32_bf16 v[130:133], v[168:171], v[182:185], 0
	v_mfma_f32_16x16x32_bf16 v[118:121], v[160:163], v[190:193], 0
	v_mfma_f32_16x16x32_bf16 v[114:117], v[168:171], v[190:193], 0
	v_mfma_f32_16x16x32_bf16 v[102:105], v[160:163], v[198:201], 0
	v_mfma_f32_16x16x32_bf16 v[98:101], v[168:171], v[198:201], 0
	v_mfma_f32_16x16x32_bf16 v[134:137], v[164:167], v[186:189], v[134:137]
	v_mfma_f32_16x16x32_bf16 v[130:133], v[172:175], v[186:189], v[130:133]
	v_mfma_f32_16x16x32_bf16 v[118:121], v[164:167], v[194:197], v[118:121]
	v_mfma_f32_16x16x32_bf16 v[114:117], v[172:175], v[194:197], v[114:117]
	v_mfma_f32_16x16x32_bf16 v[102:105], v[164:167], v[224:227], v[102:105]
	v_mfma_f32_16x16x32_bf16 v[98:101], v[172:175], v[224:227], v[98:101]
	s_barrier
	s_setprio 0
	s_add_i32 s72, 0, 0x14000
	s_add_i32 s70, s70, s18
	v_add_u32_e32 v96, s72, v157
	v_lshl_add_u64 v[154:155], s[54:55], 0, v[142:143]
	s_mov_b32 m0, s70
	ds_read_b128 v[228:231], v96
	ds_read_b128 v[232:235], v96 offset:1024
	ds_read_b128 v[236:239], v96 offset:2048
	ds_read_b128 v[240:243], v96 offset:3072
	global_load_lds_dwordx4 v142, s[54:55]
	v_lshl_add_u64 v[176:177], s[54:55], 0, v[138:139]
	s_add_i32 m0, s70, 0x2000
	s_nop 0
	global_load_lds_dwordx4 v138, s[54:55]
	s_setprio 1
	s_barrier
	s_waitcnt lgkmcnt(0)
	v_mfma_f32_16x16x32_bf16 v[126:129], v[228:231], v[182:185], 0
	v_mfma_f32_16x16x32_bf16 v[122:125], v[236:239], v[182:185], 0
	v_mfma_f32_16x16x32_bf16 v[110:113], v[228:231], v[190:193], 0
	s_mov_b32 m0, s28
	v_mfma_f32_16x16x32_bf16 v[106:109], v[236:239], v[190:193], 0
	v_lshl_add_u64 v[202:203], s[56:57], 0, v[144:145]
	v_mfma_f32_16x16x32_bf16 v[92:95], v[228:231], v[198:201], 0
	v_mfma_f32_16x16x32_bf16 v[88:91], v[236:239], v[198:201], 0
	v_mfma_f32_16x16x32_bf16 v[126:129], v[232:235], v[186:189], v[126:129]
	v_mfma_f32_16x16x32_bf16 v[122:125], v[240:243], v[186:189], v[122:125]
	v_mfma_f32_16x16x32_bf16 v[110:113], v[232:235], v[194:197], v[110:113]
	v_mfma_f32_16x16x32_bf16 v[106:109], v[240:243], v[194:197], v[106:109]
	v_mfma_f32_16x16x32_bf16 v[92:95], v[232:235], v[224:227], v[92:95]
	v_mfma_f32_16x16x32_bf16 v[88:91], v[240:243], v[224:227], v[88:91]
	s_barrier
	s_setprio 0
	ds_read_b128 v[182:185], v159 offset:16384
	ds_read_b128 v[186:189], v159 offset:17408
	ds_read_b128 v[190:193], v159 offset:18432
	ds_read_b128 v[194:197], v159 offset:19456
	ds_read_b128 v[198:201], v159 offset:20480
	ds_read_b128 v[224:227], v159 offset:21504
	global_load_lds_dwordx4 v144, s[56:57]
	v_lshl_add_u64 v[244:245], s[56:57], 0, v[140:141]
	s_mov_b32 m0, s37
	s_mov_b64 exec, s[98:99]
	global_load_lds_dwordx4 v140, s[56:57]
	s_mov_b64 exec, -1
	s_waitcnt vmcnt(10)
	s_setprio 1
	s_barrier
	s_waitcnt lgkmcnt(0)
	v_mfma_f32_16x16x32_bf16 v[84:87], v[160:163], v[182:185], 0
	v_mfma_f32_16x16x32_bf16 v[80:83], v[168:171], v[182:185], 0
	v_mfma_f32_16x16x32_bf16 v[68:71], v[160:163], v[190:193], 0
	v_mfma_f32_16x16x32_bf16 v[64:67], v[168:171], v[190:193], 0
	v_mfma_f32_16x16x32_bf16 v[28:31], v[160:163], v[198:201], 0
	v_mfma_f32_16x16x32_bf16 v[24:27], v[168:171], v[198:201], 0
	v_mfma_f32_16x16x32_bf16 v[84:87], v[164:167], v[186:189], v[84:87]
	v_mfma_f32_16x16x32_bf16 v[80:83], v[172:175], v[186:189], v[80:83]
	v_mfma_f32_16x16x32_bf16 v[68:71], v[164:167], v[194:197], v[68:71]
	v_mfma_f32_16x16x32_bf16 v[64:67], v[172:175], v[194:197], v[64:67]
	v_mfma_f32_16x16x32_bf16 v[28:31], v[164:167], v[224:227], v[28:31]
	v_mfma_f32_16x16x32_bf16 v[24:27], v[172:175], v[224:227], v[24:27]
	s_barrier
	s_setprio 0
	v_add_u32_e32 v96, 0x18000, v157
	ds_read_b128 v[160:163], v96
	ds_read_b128 v[164:167], v96 offset:1024
	ds_read_b128 v[168:171], v96 offset:2048
	ds_read_b128 v[172:175], v96 offset:3072
	s_add_u32 s70, s54, 0x40000
	s_addc_u32 s71, s55, 0
	s_add_i32 s72, s72, s18
	s_mov_b32 m0, s72
	s_nop 0
	global_load_lds_dwordx4 v142, s[70:71]
	s_add_i32 m0, s72, 0x2000
	s_nop 0
	global_load_lds_dwordx4 v138, s[70:71]
	s_waitcnt vmcnt(6)
	s_setprio 1
	s_barrier
	v_mfma_f32_16x16x32_bf16 v[76:79], v[228:231], v[182:185], 0
	v_mfma_f32_16x16x32_bf16 v[72:75], v[236:239], v[182:185], 0
	v_mfma_f32_16x16x32_bf16 v[60:63], v[228:231], v[190:193], 0
	s_add_i32 s70, 0, 0x18000
	v_mfma_f32_16x16x32_bf16 v[56:59], v[236:239], v[190:193], 0
	v_add_u32_e32 v96, s70, v157
	v_mfma_f32_16x16x32_bf16 v[20:23], v[228:231], v[198:201], 0
	v_mfma_f32_16x16x32_bf16 v[16:19], v[236:239], v[198:201], 0
	v_mfma_f32_16x16x32_bf16 v[76:79], v[232:235], v[186:189], v[76:79]
	v_mfma_f32_16x16x32_bf16 v[72:75], v[240:243], v[186:189], v[72:75]
	v_mfma_f32_16x16x32_bf16 v[60:63], v[232:235], v[194:197], v[60:63]
	v_mfma_f32_16x16x32_bf16 v[56:59], v[240:243], v[194:197], v[56:59]
	v_mfma_f32_16x16x32_bf16 v[20:23], v[232:235], v[224:227], v[20:23]
	v_mfma_f32_16x16x32_bf16 v[16:19], v[240:243], v[224:227], v[16:19]
	s_barrier
	s_setprio 0
	s_add_u32 s56, s56, 0x30000
	s_addc_u32 s57, s57, 0
	s_mov_b32 m0, s58
	ds_read_b128 v[182:185], v159 offset:32768
	ds_read_b128 v[186:189], v159 offset:33792
	ds_read_b128 v[190:193], v159 offset:34816
	ds_read_b128 v[194:197], v159 offset:35840
	ds_read_b128 v[198:201], v159 offset:36864
	ds_read_b128 v[224:227], v159 offset:37888
	global_load_lds_dwordx4 v144, s[56:57]
	s_mov_b32 m0, s59
	s_mov_b64 exec, s[98:99]
	global_load_lds_dwordx4 v140, s[56:57]
	s_mov_b64 exec, -1
	s_setprio 1
	s_barrier
	s_waitcnt lgkmcnt(0)
	v_mfma_f32_16x16x32_bf16 v[134:137], v[160:163], v[182:185], v[134:137]
	v_mfma_f32_16x16x32_bf16 v[130:133], v[168:171], v[182:185], v[130:133]
	v_mfma_f32_16x16x32_bf16 v[118:121], v[160:163], v[190:193], v[118:121]
	v_mfma_f32_16x16x32_bf16 v[114:117], v[168:171], v[190:193], v[114:117]
	v_mfma_f32_16x16x32_bf16 v[102:105], v[160:163], v[198:201], v[102:105]
	v_mfma_f32_16x16x32_bf16 v[98:101], v[168:171], v[198:201], v[98:101]
	v_mfma_f32_16x16x32_bf16 v[134:137], v[164:167], v[186:189], v[134:137]
	v_mfma_f32_16x16x32_bf16 v[130:133], v[172:175], v[186:189], v[130:133]
	v_mfma_f32_16x16x32_bf16 v[118:121], v[164:167], v[194:197], v[118:121]
	v_mfma_f32_16x16x32_bf16 v[114:117], v[172:175], v[194:197], v[114:117]
	v_mfma_f32_16x16x32_bf16 v[102:105], v[164:167], v[224:227], v[102:105]
	v_mfma_f32_16x16x32_bf16 v[98:101], v[172:175], v[224:227], v[98:101]
	s_barrier
	s_setprio 0
	s_add_i32 s56, 0, 0x1c000
	s_add_i32 s57, s70, s18
	v_add_u32_e32 v96, s56, v157
	v_lshl_add_u64 v[154:155], v[154:155], 0, s[6:7]
	s_mov_b32 m0, s57
	ds_read_b128 v[228:231], v96
	ds_read_b128 v[232:235], v96 offset:1024
	ds_read_b128 v[236:239], v96 offset:2048
	ds_read_b128 v[240:243], v96 offset:3072
	global_load_lds_dwordx4 v[154:155], off
	v_lshl_add_u64 v[154:155], v[176:177], 0, s[6:7]
	s_add_i32 m0, s57, 0x2000
	s_nop 0
	global_load_lds_dwordx4 v[154:155], off
	s_setprio 1
	s_barrier
	s_waitcnt lgkmcnt(0)
	v_mfma_f32_16x16x32_bf16 v[126:129], v[228:231], v[182:185], v[126:129]
	v_mfma_f32_16x16x32_bf16 v[122:125], v[236:239], v[182:185], v[122:125]
	v_mfma_f32_16x16x32_bf16 v[110:113], v[228:231], v[190:193], v[110:113]
	s_mov_b32 m0, s60
	v_mfma_f32_16x16x32_bf16 v[106:109], v[236:239], v[190:193], v[106:109]
	v_lshl_add_u64 v[154:155], v[202:203], 0, s[6:7]
	v_mfma_f32_16x16x32_bf16 v[92:95], v[228:231], v[198:201], v[92:95]
	v_mfma_f32_16x16x32_bf16 v[88:91], v[236:239], v[198:201], v[88:91]
	v_mfma_f32_16x16x32_bf16 v[126:129], v[232:235], v[186:189], v[126:129]
	v_mfma_f32_16x16x32_bf16 v[122:125], v[240:243], v[186:189], v[122:125]
	v_mfma_f32_16x16x32_bf16 v[110:113], v[232:235], v[194:197], v[110:113]
	v_mfma_f32_16x16x32_bf16 v[106:109], v[240:243], v[194:197], v[106:109]
	v_mfma_f32_16x16x32_bf16 v[92:95], v[232:235], v[224:227], v[92:95]
	v_mfma_f32_16x16x32_bf16 v[88:91], v[240:243], v[224:227], v[88:91]
	s_barrier
	s_setprio 0
	ds_read_b128 v[182:185], v159 offset:49152
	ds_read_b128 v[186:189], v159 offset:50176
	ds_read_b128 v[190:193], v159 offset:51200
	ds_read_b128 v[194:197], v159 offset:52224
	ds_read_b128 v[198:201], v159 offset:53248
	ds_read_b128 v[224:227], v159 offset:54272
	global_load_lds_dwordx4 v[154:155], off
	v_lshl_add_u64 v[154:155], v[244:245], 0, s[6:7]
	s_mov_b32 m0, s61
	s_mov_b64 exec, s[98:99]
	global_load_lds_dwordx4 v[154:155], off
	s_mov_b64 exec, -1
	s_waitcnt vmcnt(10)
	s_setprio 1
	s_barrier
	s_waitcnt lgkmcnt(0)
	v_mfma_f32_16x16x32_bf16 v[84:87], v[160:163], v[182:185], v[84:87]
	v_mfma_f32_16x16x32_bf16 v[80:83], v[168:171], v[182:185], v[80:83]
	v_mfma_f32_16x16x32_bf16 v[68:71], v[160:163], v[190:193], v[68:71]
	v_mfma_f32_16x16x32_bf16 v[64:67], v[168:171], v[190:193], v[64:67]
	v_mfma_f32_16x16x32_bf16 v[28:31], v[160:163], v[198:201], v[28:31]
	v_mfma_f32_16x16x32_bf16 v[24:27], v[168:171], v[198:201], v[24:27]
	v_mfma_f32_16x16x32_bf16 v[84:87], v[164:167], v[186:189], v[84:87]
	v_mfma_f32_16x16x32_bf16 v[80:83], v[172:175], v[186:189], v[80:83]
	v_mfma_f32_16x16x32_bf16 v[68:71], v[164:167], v[194:197], v[68:71]
	v_mfma_f32_16x16x32_bf16 v[64:67], v[172:175], v[194:197], v[64:67]
	v_mfma_f32_16x16x32_bf16 v[28:31], v[164:167], v[224:227], v[28:31]
	v_mfma_f32_16x16x32_bf16 v[24:27], v[172:175], v[224:227], v[24:27]
	s_barrier
	s_setprio 0
	v_add_u32_e32 v96, 0x10000, v157
	ds_read_b128 v[160:163], v96
	ds_read_b128 v[164:167], v96 offset:1024
	ds_read_b128 v[168:171], v96 offset:2048
	ds_read_b128 v[172:175], v96 offset:3072
	s_add_u32 s54, s54, 0x40080
	s_addc_u32 s55, s55, 0
	s_add_i32 s56, s56, s18
	s_mov_b32 m0, s56
	s_nop 0
	global_load_lds_dwordx4 v142, s[54:55]
	s_add_i32 m0, s56, 0x2000
	s_nop 0
	global_load_lds_dwordx4 v138, s[54:55]
	s_waitcnt vmcnt(6)
	s_setprio 1
	s_barrier
	v_mfma_f32_16x16x32_bf16 v[76:79], v[228:231], v[182:185], v[76:79]
	v_mfma_f32_16x16x32_bf16 v[72:75], v[236:239], v[182:185], v[72:75]
	v_mfma_f32_16x16x32_bf16 v[60:63], v[228:231], v[190:193], v[60:63]
	s_add_i32 s69, s69, 2
	v_mfma_f32_16x16x32_bf16 v[56:59], v[236:239], v[190:193], v[56:59]
	s_add_u32 s42, s42, 0x100
	v_mfma_f32_16x16x32_bf16 v[20:23], v[228:231], v[198:201], v[20:23]
	s_addc_u32 s43, s43, 0
	v_mfma_f32_16x16x32_bf16 v[16:19], v[236:239], v[198:201], v[16:19]
	s_add_u32 s67, s67, 0x100
	v_mfma_f32_16x16x32_bf16 v[76:79], v[232:235], v[186:189], v[76:79]
	s_addc_u32 s68, s68, 0
	v_mfma_f32_16x16x32_bf16 v[72:75], v[240:243], v[186:189], v[72:75]
	s_cmp_gt_u32 s69, 13
	v_mfma_f32_16x16x32_bf16 v[60:63], v[232:235], v[194:197], v[60:63]
	v_mfma_f32_16x16x32_bf16 v[56:59], v[240:243], v[194:197], v[56:59]
	v_mfma_f32_16x16x32_bf16 v[20:23], v[232:235], v[224:227], v[20:23]
	v_mfma_f32_16x16x32_bf16 v[16:19], v[240:243], v[224:227], v[16:19]
	s_barrier
	s_setprio 0

.LBB0_464:
	s_ashr_i32 s51, s50, 31
	s_lshl_b64 s[54:55], s[50:51], 19
	s_add_u32 s54, s10, s54
	s_addc_u32 s55, s11, s55
	s_and_b64 s[42:43], s[42:43], exec
	s_cselect_b32 s51, s55, s59
	s_cselect_b32 s68, s54, s58
	s_add_u32 s42, s60, 0x30080
	s_addc_u32 s43, s61, 0
	s_add_u32 s69, s58, 0x100
	s_addc_u32 s70, s59, 0
	s_mov_b32 s71, -2
	v_add_u32_e32 v96, 0x10000, v163
	ds_read_b128 v[154:157], v96
	ds_read_b128 v[170:173], v96 offset:1024
	ds_read_b128 v[174:177], v96 offset:2048
	ds_read_b128 v[182:185], v96 offset:3072
	s_add_u32 s58, s42, 0xfffd0080
	s_addc_u32 s59, s43, -1
	s_add_i32 s72, 0, 0x10000
	v_add_u32_e32 v96, s72, v163
	s_cmp_eq_u32 s71, 12
	s_cselect_b32 s61, s53, s59
	s_cselect_b32 s60, s52, s58
	s_cselect_b32 s59, s51, s70
	s_cselect_b32 s58, s68, s69
	s_add_i32 m0, s27, 0xc000
	ds_read_b128 v[186:189], v168
	ds_read_b128 v[190:193], v168 offset:1024
	ds_read_b128 v[194:197], v168 offset:2048
	ds_read_b128 v[198:201], v168 offset:3072
	ds_read_b128 v[224:227], v168 offset:4096
	ds_read_b128 v[228:231], v168 offset:5120
	global_load_lds_dwordx4 v150, s[42:43]
	s_add_i32 m0, s27, 0xe000
	s_mov_b64 exec, s[98:99]
	global_load_lds_dwordx4 v152, s[42:43]
	s_mov_b64 exec, -1
	s_setprio 1
	s_barrier
	s_waitcnt lgkmcnt(0)
	v_mfma_f32_16x16x32_bf16 v[134:137], v[154:157], v[186:189], 0
	v_mfma_f32_16x16x32_bf16 v[130:133], v[174:177], v[186:189], 0
	v_mfma_f32_16x16x32_bf16 v[92:95], v[154:157], v[194:197], 0
	v_mfma_f32_16x16x32_bf16 v[88:91], v[174:177], v[194:197], 0
	v_mfma_f32_16x16x32_bf16 v[76:79], v[154:157], v[224:227], 0
	v_mfma_f32_16x16x32_bf16 v[72:75], v[174:177], v[224:227], 0
	v_mfma_f32_16x16x32_bf16 v[134:137], v[170:173], v[190:193], v[134:137]
	v_mfma_f32_16x16x32_bf16 v[130:133], v[182:185], v[190:193], v[130:133]
	v_mfma_f32_16x16x32_bf16 v[92:95], v[170:173], v[198:201], v[92:95]
	v_mfma_f32_16x16x32_bf16 v[88:91], v[182:185], v[198:201], v[88:91]
	v_mfma_f32_16x16x32_bf16 v[76:79], v[170:173], v[228:231], v[76:79]
	v_mfma_f32_16x16x32_bf16 v[72:75], v[182:185], v[228:231], v[72:75]
	s_barrier
	s_setprio 0
	s_add_i32 s80, 0, 0x14000
	s_add_i32 s72, s72, s18
	v_add_u32_e32 v96, s80, v163
	v_lshl_add_u64 v[160:161], s[58:59], 0, v[140:141]
	s_mov_b32 m0, s72
	ds_read_b128 v[232:235], v96
	ds_read_b128 v[236:239], v96 offset:1024
	ds_read_b128 v[240:243], v96 offset:2048
	ds_read_b128 v[244:247], v96 offset:3072
	global_load_lds_dwordx4 v140, s[58:59]
	v_lshl_add_u64 v[164:165], s[58:59], 0, v[144:145]
	s_add_i32 m0, s72, 0x2000
	s_nop 0
	global_load_lds_dwordx4 v144, s[58:59]
	s_setprio 1
	s_barrier
	s_waitcnt lgkmcnt(0)
	v_mfma_f32_16x16x32_bf16 v[110:113], v[232:235], v[186:189], 0
	v_mfma_f32_16x16x32_bf16 v[98:101], v[240:243], v[186:189], 0
	v_mfma_f32_16x16x32_bf16 v[84:87], v[232:235], v[194:197], 0
	s_mov_b32 m0, s27
	v_mfma_f32_16x16x32_bf16 v[80:83], v[240:243], v[194:197], 0
	v_lshl_add_u64 v[202:203], s[60:61], 0, v[138:139]
	v_mfma_f32_16x16x32_bf16 v[68:71], v[232:235], v[224:227], 0
	v_mfma_f32_16x16x32_bf16 v[64:67], v[240:243], v[224:227], 0
	v_mfma_f32_16x16x32_bf16 v[110:113], v[236:239], v[190:193], v[110:113]
	v_mfma_f32_16x16x32_bf16 v[98:101], v[244:247], v[190:193], v[98:101]
	v_mfma_f32_16x16x32_bf16 v[84:87], v[236:239], v[198:201], v[84:87]
	v_mfma_f32_16x16x32_bf16 v[80:83], v[244:247], v[198:201], v[80:83]
	v_mfma_f32_16x16x32_bf16 v[68:71], v[236:239], v[228:231], v[68:71]
	v_mfma_f32_16x16x32_bf16 v[64:67], v[244:247], v[228:231], v[64:67]
	s_barrier
	s_setprio 0
	ds_read_b128 v[186:189], v168 offset:16384
	ds_read_b128 v[190:193], v168 offset:17408
	ds_read_b128 v[194:197], v168 offset:18432
	ds_read_b128 v[198:201], v168 offset:19456
	ds_read_b128 v[224:227], v168 offset:20480
	ds_read_b128 v[228:231], v168 offset:21504
	global_load_lds_dwordx4 v138, s[60:61]
	v_lshl_add_u64 v[248:249], s[60:61], 0, v[142:143]
	s_mov_b32 m0, s28
	s_mov_b64 exec, s[98:99]
	global_load_lds_dwordx4 v142, s[60:61]
	s_mov_b64 exec, -1
	s_waitcnt vmcnt(10)
	s_setprio 1
	s_barrier
	s_waitcnt lgkmcnt(0)
	v_mfma_f32_16x16x32_bf16 v[60:63], v[154:157], v[186:189], 0
	v_mfma_f32_16x16x32_bf16 v[56:59], v[174:177], v[186:189], 0
	v_mfma_f32_16x16x32_bf16 v[44:47], v[154:157], v[194:197], 0
	v_mfma_f32_16x16x32_bf16 v[40:43], v[174:177], v[194:197], 0
	v_mfma_f32_16x16x32_bf16 v[28:31], v[154:157], v[224:227], 0
	v_mfma_f32_16x16x32_bf16 v[24:27], v[174:177], v[224:227], 0
	v_mfma_f32_16x16x32_bf16 v[60:63], v[170:173], v[190:193], v[60:63]
	v_mfma_f32_16x16x32_bf16 v[56:59], v[182:185], v[190:193], v[56:59]
	v_mfma_f32_16x16x32_bf16 v[44:47], v[170:173], v[198:201], v[44:47]
	v_mfma_f32_16x16x32_bf16 v[40:43], v[182:185], v[198:201], v[40:43]
	v_mfma_f32_16x16x32_bf16 v[28:31], v[170:173], v[228:231], v[28:31]
	v_mfma_f32_16x16x32_bf16 v[24:27], v[182:185], v[228:231], v[24:27]
	s_barrier
	s_setprio 0
	v_add_u32_e32 v96, 0x18000, v163
	ds_read_b128 v[154:157], v96
	ds_read_b128 v[170:173], v96 offset:1024
	ds_read_b128 v[174:177], v96 offset:2048
	ds_read_b128 v[182:185], v96 offset:3072
	s_add_u32 s78, s58, 0x40000
	s_addc_u32 s79, s59, 0
	s_add_i32 s72, s80, s18
	s_mov_b32 m0, s72
	s_nop 0
	global_load_lds_dwordx4 v140, s[78:79]
	s_add_i32 m0, s72, 0x2000
	s_nop 0
	global_load_lds_dwordx4 v144, s[78:79]
	s_waitcnt vmcnt(6)
	s_setprio 1
	s_barrier
	v_mfma_f32_16x16x32_bf16 v[52:55], v[232:235], v[186:189], 0
	v_mfma_f32_16x16x32_bf16 v[48:51], v[240:243], v[186:189], 0
	v_mfma_f32_16x16x32_bf16 v[36:39], v[232:235], v[194:197], 0
	s_add_i32 s72, 0, 0x18000
	v_mfma_f32_16x16x32_bf16 v[32:35], v[240:243], v[194:197], 0
	v_add_u32_e32 v96, s72, v163
	v_mfma_f32_16x16x32_bf16 v[20:23], v[232:235], v[224:227], 0
	v_mfma_f32_16x16x32_bf16 v[16:19], v[240:243], v[224:227], 0
	v_mfma_f32_16x16x32_bf16 v[52:55], v[236:239], v[190:193], v[52:55]
	v_mfma_f32_16x16x32_bf16 v[48:51], v[244:247], v[190:193], v[48:51]
	v_mfma_f32_16x16x32_bf16 v[36:39], v[236:239], v[198:201], v[36:39]
	v_mfma_f32_16x16x32_bf16 v[32:35], v[244:247], v[198:201], v[32:35]
	v_mfma_f32_16x16x32_bf16 v[20:23], v[236:239], v[228:231], v[20:23]
	v_mfma_f32_16x16x32_bf16 v[16:19], v[244:247], v[228:231], v[16:19]
	s_barrier
	s_setprio 0
	s_add_u32 s60, s60, 0x30000
	s_addc_u32 s61, s61, 0
	s_mov_b32 m0, s37
	ds_read_b128 v[186:189], v168 offset:32768
	ds_read_b128 v[190:193], v168 offset:33792
	ds_read_b128 v[194:197], v168 offset:34816
	ds_read_b128 v[198:201], v168 offset:35840
	ds_read_b128 v[224:227], v168 offset:36864
	ds_read_b128 v[228:231], v168 offset:37888
	global_load_lds_dwordx4 v138, s[60:61]
	s_mov_b32 m0, s57
	s_mov_b64 exec, s[98:99]
	global_load_lds_dwordx4 v142, s[60:61]
	s_mov_b64 exec, -1
	s_setprio 1
	s_barrier
	s_waitcnt lgkmcnt(0)
	v_mfma_f32_16x16x32_bf16 v[134:137], v[154:157], v[186:189], v[134:137]
	v_mfma_f32_16x16x32_bf16 v[130:133], v[174:177], v[186:189], v[130:133]
	v_mfma_f32_16x16x32_bf16 v[92:95], v[154:157], v[194:197], v[92:95]
	v_mfma_f32_16x16x32_bf16 v[88:91], v[174:177], v[194:197], v[88:91]
	v_mfma_f32_16x16x32_bf16 v[76:79], v[154:157], v[224:227], v[76:79]
	v_mfma_f32_16x16x32_bf16 v[72:75], v[174:177], v[224:227], v[72:75]
	v_mfma_f32_16x16x32_bf16 v[134:137], v[170:173], v[190:193], v[134:137]
	v_mfma_f32_16x16x32_bf16 v[130:133], v[182:185], v[190:193], v[130:133]
	v_mfma_f32_16x16x32_bf16 v[92:95], v[170:173], v[198:201], v[92:95]
	v_mfma_f32_16x16x32_bf16 v[88:91], v[182:185], v[198:201], v[88:91]
	v_mfma_f32_16x16x32_bf16 v[76:79], v[170:173], v[228:231], v[76:79]
	v_mfma_f32_16x16x32_bf16 v[72:75], v[182:185], v[228:231], v[72:75]
	s_barrier
	s_setprio 0
	s_add_i32 s60, 0, 0x1c000
	s_add_i32 s61, s72, s18
	v_add_u32_e32 v96, s60, v163
	v_lshl_add_u64 v[160:161], v[160:161], 0, s[6:7]
	s_mov_b32 m0, s61
	ds_read_b128 v[232:235], v96
	ds_read_b128 v[236:239], v96 offset:1024
	ds_read_b128 v[240:243], v96 offset:2048
	ds_read_b128 v[244:247], v96 offset:3072
	global_load_lds_dwordx4 v[160:161], off
	v_lshl_add_u64 v[160:161], v[164:165], 0, s[6:7]
	s_add_i32 m0, s61, 0x2000
	s_nop 0
	global_load_lds_dwordx4 v[160:161], off
	s_setprio 1
	s_barrier
	s_waitcnt lgkmcnt(0)
	v_mfma_f32_16x16x32_bf16 v[110:113], v[232:235], v[186:189], v[110:113]
	v_mfma_f32_16x16x32_bf16 v[98:101], v[240:243], v[186:189], v[98:101]
	v_mfma_f32_16x16x32_bf16 v[84:87], v[232:235], v[194:197], v[84:87]
	s_mov_b32 m0, s62
	v_mfma_f32_16x16x32_bf16 v[80:83], v[240:243], v[194:197], v[80:83]
	v_lshl_add_u64 v[160:161], v[202:203], 0, s[6:7]
	v_mfma_f32_16x16x32_bf16 v[68:71], v[232:235], v[224:227], v[68:71]
	v_mfma_f32_16x16x32_bf16 v[64:67], v[240:243], v[224:227], v[64:67]
	v_mfma_f32_16x16x32_bf16 v[110:113], v[236:239], v[190:193], v[110:113]
	v_mfma_f32_16x16x32_bf16 v[98:101], v[244:247], v[190:193], v[98:101]
	v_mfma_f32_16x16x32_bf16 v[84:87], v[236:239], v[198:201], v[84:87]
	v_mfma_f32_16x16x32_bf16 v[80:83], v[244:247], v[198:201], v[80:83]
	v_mfma_f32_16x16x32_bf16 v[68:71], v[236:239], v[228:231], v[68:71]
	v_mfma_f32_16x16x32_bf16 v[64:67], v[244:247], v[228:231], v[64:67]
	s_barrier
	s_setprio 0
	ds_read_b128 v[186:189], v168 offset:49152
	ds_read_b128 v[190:193], v168 offset:50176
	ds_read_b128 v[194:197], v168 offset:51200
	ds_read_b128 v[198:201], v168 offset:52224
	ds_read_b128 v[224:227], v168 offset:53248
	ds_read_b128 v[228:231], v168 offset:54272
	global_load_lds_dwordx4 v[160:161], off
	v_lshl_add_u64 v[160:161], v[248:249], 0, s[6:7]
	s_mov_b32 m0, s63
	s_mov_b64 exec, s[98:99]
	global_load_lds_dwordx4 v[160:161], off
	s_mov_b64 exec, -1
	s_waitcnt vmcnt(10)
	s_setprio 1
	s_barrier
	s_waitcnt lgkmcnt(0)
	v_mfma_f32_16x16x32_bf16 v[60:63], v[154:157], v[186:189], v[60:63]
	v_mfma_f32_16x16x32_bf16 v[56:59], v[174:177], v[186:189], v[56:59]
	v_mfma_f32_16x16x32_bf16 v[44:47], v[154:157], v[194:197], v[44:47]
	v_mfma_f32_16x16x32_bf16 v[40:43], v[174:177], v[194:197], v[40:43]
	v_mfma_f32_16x16x32_bf16 v[28:31], v[154:157], v[224:227], v[28:31]
	v_mfma_f32_16x16x32_bf16 v[24:27], v[174:177], v[224:227], v[24:27]
	v_mfma_f32_16x16x32_bf16 v[60:63], v[170:173], v[190:193], v[60:63]
	v_mfma_f32_16x16x32_bf16 v[56:59], v[182:185], v[190:193], v[56:59]
	v_mfma_f32_16x16x32_bf16 v[44:47], v[170:173], v[198:201], v[44:47]
	v_mfma_f32_16x16x32_bf16 v[40:43], v[182:185], v[198:201], v[40:43]
	v_mfma_f32_16x16x32_bf16 v[28:31], v[170:173], v[228:231], v[28:31]
	v_mfma_f32_16x16x32_bf16 v[24:27], v[182:185], v[228:231], v[24:27]
	s_barrier
	s_setprio 0
	v_add_u32_e32 v96, 0x10000, v163
	ds_read_b128 v[154:157], v96
	ds_read_b128 v[170:173], v96 offset:1024
	ds_read_b128 v[174:177], v96 offset:2048
	ds_read_b128 v[182:185], v96 offset:3072
	s_add_u32 s58, s58, 0x40080
	s_addc_u32 s59, s59, 0
	s_add_i32 s60, s60, s18
	s_mov_b32 m0, s60
	s_nop 0
	global_load_lds_dwordx4 v140, s[58:59]
	s_add_i32 m0, s60, 0x2000
	s_nop 0
	global_load_lds_dwordx4 v144, s[58:59]
	s_waitcnt vmcnt(6)
	s_setprio 1
	s_barrier
	v_mfma_f32_16x16x32_bf16 v[52:55], v[232:235], v[186:189], v[52:55]
	v_mfma_f32_16x16x32_bf16 v[48:51], v[240:243], v[186:189], v[48:51]
	v_mfma_f32_16x16x32_bf16 v[36:39], v[232:235], v[194:197], v[36:39]
	s_add_i32 s71, s71, 2
	v_mfma_f32_16x16x32_bf16 v[32:35], v[240:243], v[194:197], v[32:35]
	s_add_u32 s42, s42, 0x100
	v_mfma_f32_16x16x32_bf16 v[20:23], v[232:235], v[224:227], v[20:23]
	s_addc_u32 s43, s43, 0
	v_mfma_f32_16x16x32_bf16 v[16:19], v[240:243], v[224:227], v[16:19]
	s_add_u32 s69, s69, 0x100
	v_mfma_f32_16x16x32_bf16 v[52:55], v[236:239], v[190:193], v[52:55]
	s_addc_u32 s70, s70, 0
	v_mfma_f32_16x16x32_bf16 v[48:51], v[244:247], v[190:193], v[48:51]
	s_cmp_gt_u32 s71, 13
	v_mfma_f32_16x16x32_bf16 v[36:39], v[236:239], v[198:201], v[36:39]
	v_mfma_f32_16x16x32_bf16 v[32:35], v[244:247], v[198:201], v[32:35]
	v_mfma_f32_16x16x32_bf16 v[20:23], v[236:239], v[228:231], v[20:23]
	v_mfma_f32_16x16x32_bf16 v[16:19], v[244:247], v[228:231], v[16:19]
	s_barrier
	s_setprio 0

.LBB0_675:
	s_or_b32 s2, s17, 1
	s_cmp_eq_u32 s39, 0
	s_cselect_b64 s[60:61], -1, 0
	s_cmp_lg_u32 s39, 0
	s_cselect_b64 s[58:59], -1, 0
	s_or_b32 s3, s38, s39
	s_cmp_lg_u32 s3, 0
	s_cbranch_scc0 .LBB0_690
	s_cmp_lg_u32 s38, 2
	s_cselect_b64 s[4:5], -1, 0
	s_xor_b64 s[10:11], s[60:61], -1
	s_or_b64 s[4:5], s[10:11], s[4:5]
	s_and_b64 vcc, exec, s[4:5]
	s_mov_b64 s[74:75], s[62:63]
	s_cbranch_vccnz .LBB0_770
	s_waitcnt lgkmcnt(0)
	s_mov_b64 s[40:41], s[92:93]
	s_cmp_ge_i32 s2, s40
	s_cselect_b64 s[4:5], -1, 0
	s_cmp_lt_i32 s2, s41
	s_cselect_b64 s[10:11], -1, 0
	s_and_b64 s[4:5], s[4:5], s[10:11]
	s_andn2_b64 vcc, exec, s[4:5]
	s_mov_b64 s[74:75], s[62:63]
	s_mov_b64 s[42:43], s[94:95]
	s_cbranch_vccnz .LBB0_770
	s_andn2_b64 vcc, exec, s[62:63]
	s_cbranch_vccnz .LBB0_739
	s_waitcnt vmcnt(0)
	s_barrier
	s_mov_b64 s[40:41], exec
	v_readlane_b32 s4, v254, 0
	v_readlane_b32 s5, v254, 1
	s_and_b64 s[4:5], s[40:41], s[4:5]
	s_mov_b64 exec, s[4:5]
	s_cbranch_execz .LBB0_738
	v_readlane_b32 s3, v255, 34
	s_waitcnt vmcnt(0) expcnt(0) lgkmcnt(0)
	s_nop 0
	v_mov_b32_e32 v0, s3
	ds_read_b32 v2, v0
	v_readlane_b32 s3, v255, 35
	s_waitcnt lgkmcnt(0)
	v_cmp_ne_u32_e32 vcc, 0, v2
	v_mov_b32_e32 v0, s3
	ds_read_b32 v0, v0
	s_cbranch_vccnz .LBB0_706
	s_mov_b32 s3, 1
	s_branch .LBB0_683
.Lhl_back_tramp:
	s_branch .LBB0_182
.LBB0_682:
	s_and_b64 vcc, exec, s[44:45]
	s_cbranch_vccnz .LBB0_701

.LBB0_1020:
	s_add_u32 s44, s84, 0x80
	s_addc_u32 s45, s85, 0
	s_add_u32 s87, s46, 0x100
	s_addc_u32 vcc_lo, s47, 0
	s_mov_b32 s46, 0
	s_waitcnt vmcnt(0)
	v_add_u32_e32 v96, 0x10000, v225
	ds_read_b128 v[80:83], v96 offset:2048
	ds_read_b128 v[98:101], v96 offset:3072
	s_add_i32 vcc_hi, s46, 2
	s_add_u32 s84, s44, 0x80
	s_addc_u32 s47, s45, 0
	s_add_i32 s29, 0, 0x10000
	v_add_u32_e32 v96, s29, v225
	ds_read_b128 v[56:59], v96
	ds_read_b128 v[68:71], v96 offset:1024
	s_cmp_eq_u32 s90, s46
	s_cselect_b32 s46, s80, s84
	s_cselect_b32 s47, s81, s47
	s_cselect_b32 s85, s83, vcc_lo
	s_cselect_b32 s84, s82, s87
	s_add_i32 m0, s2, 0xc000
	ds_read_b128 v[102:105], v227
	ds_read_b128 v[112:115], v227 offset:1024
	ds_read_b128 v[124:127], v227 offset:2048
	ds_read_b128 v[192:195], v227 offset:3072
	ds_read_b128 v[196:199], v227 offset:4096
	ds_read_b128 v[200:203], v227 offset:5120
	global_load_lds_dwordx4 v188, s[44:45]
	s_add_i32 m0, s2, 0xe000
	s_mov_b64 exec, s[98:99]
	global_load_lds_dwordx4 v190, s[44:45]
	s_mov_b64 exec, -1
	s_waitcnt lgkmcnt(6)
	s_setprio 1
	s_barrier
	s_waitcnt lgkmcnt(0)
	v_mfma_f32_16x16x32_bf16 v[172:175], v[56:59], v[102:105], 0
	v_mfma_f32_16x16x32_bf16 v[168:171], v[80:83], v[102:105], 0
	v_mfma_f32_16x16x32_bf16 v[156:159], v[56:59], v[124:127], 0
	v_mfma_f32_16x16x32_bf16 v[152:155], v[80:83], v[124:127], 0
	v_mfma_f32_16x16x32_bf16 v[132:135], v[56:59], v[196:199], 0
	v_mfma_f32_16x16x32_bf16 v[128:131], v[80:83], v[196:199], 0
	v_mfma_f32_16x16x32_bf16 v[172:175], v[68:71], v[112:115], v[172:175]
	v_mfma_f32_16x16x32_bf16 v[168:171], v[98:101], v[112:115], v[168:171]
	v_mfma_f32_16x16x32_bf16 v[156:159], v[68:71], v[192:195], v[156:159]
	v_mfma_f32_16x16x32_bf16 v[152:155], v[98:101], v[192:195], v[152:155]
	v_mfma_f32_16x16x32_bf16 v[132:135], v[68:71], v[200:203], v[132:135]
	v_mfma_f32_16x16x32_bf16 v[128:131], v[98:101], v[200:203], v[128:131]
	s_barrier
	s_setprio 0
	s_add_i32 s96, 0, 0x14000
	s_add_i32 s29, s29, s18
	v_add_u32_e32 v96, s96, v225
	v_lshl_add_u64 v[106:107], s[84:85], 0, v[182:183]
	s_mov_b32 m0, s29
	ds_read_b128 v[228:231], v96
	ds_read_b128 v[232:235], v96 offset:1024
	ds_read_b128 v[236:239], v96 offset:2048
	ds_read_b128 v[240:243], v96 offset:3072
	global_load_lds_dwordx4 v182, s[84:85]
	v_lshl_add_u64 v[248:249], s[84:85], 0, v[186:187]
	s_add_i32 m0, s29, 0x2000
	s_nop 0
	global_load_lds_dwordx4 v186, s[84:85]
	s_setprio 1
	s_barrier
	s_waitcnt lgkmcnt(0)
	v_mfma_f32_16x16x32_bf16 v[164:167], v[228:231], v[102:105], 0
	v_mfma_f32_16x16x32_bf16 v[102:105], v[236:239], v[102:105], 0
	v_mfma_f32_16x16x32_bf16 v[120:123], v[228:231], v[196:199], 0
	s_mov_b32 m0, s2
	v_mfma_f32_16x16x32_bf16 v[116:119], v[236:239], v[196:199], 0
	v_lshl_add_u64 v[250:251], s[46:47], 0, v[176:177]
	v_mfma_f32_16x16x32_bf16 v[164:167], v[232:235], v[112:115], v[164:167]
	v_mfma_f32_16x16x32_bf16 v[102:105], v[240:243], v[112:115], v[102:105]
	v_mfma_f32_16x16x32_bf16 v[112:115], v[228:231], v[124:127], 0
	v_mfma_f32_16x16x32_bf16 v[124:127], v[236:239], v[124:127], 0
	v_mfma_f32_16x16x32_bf16 v[120:123], v[232:235], v[200:203], v[120:123]
	v_mfma_f32_16x16x32_bf16 v[116:119], v[240:243], v[200:203], v[116:119]
	v_mfma_f32_16x16x32_bf16 v[112:115], v[232:235], v[192:195], v[112:115]
	v_mfma_f32_16x16x32_bf16 v[124:127], v[240:243], v[192:195], v[124:127]
	s_barrier
	s_setprio 0
	ds_read_b128 v[144:147], v227 offset:16384
	ds_read_b128 v[148:151], v227 offset:17408
	ds_read_b128 v[160:163], v227 offset:18432
	ds_read_b128 v[192:195], v227 offset:19456
	ds_read_b128 v[196:199], v227 offset:20480
	ds_read_b128 v[200:203], v227 offset:21504
	global_load_lds_dwordx4 v176, s[46:47]
	v_lshl_add_u64 v[252:253], s[46:47], 0, v[184:185]
	s_mov_b32 m0, s3
	s_mov_b64 exec, s[98:99]
	global_load_lds_dwordx4 v184, s[46:47]
	s_mov_b64 exec, -1
	s_waitcnt vmcnt(10)
	s_setprio 1
	s_barrier
	s_waitcnt lgkmcnt(0)
	v_mfma_f32_16x16x32_bf16 v[88:91], v[56:59], v[144:147], 0
	v_mfma_f32_16x16x32_bf16 v[84:87], v[80:83], v[144:147], 0
	v_mfma_f32_16x16x32_bf16 v[52:55], v[56:59], v[160:163], 0
	v_mfma_f32_16x16x32_bf16 v[48:51], v[80:83], v[160:163], 0
	v_mfma_f32_16x16x32_bf16 v[28:31], v[56:59], v[196:199], 0
	v_mfma_f32_16x16x32_bf16 v[24:27], v[80:83], v[196:199], 0
	v_mfma_f32_16x16x32_bf16 v[88:91], v[68:71], v[148:151], v[88:91]
	v_mfma_f32_16x16x32_bf16 v[84:87], v[98:101], v[148:151], v[84:87]
	v_mfma_f32_16x16x32_bf16 v[52:55], v[68:71], v[192:195], v[52:55]
	v_mfma_f32_16x16x32_bf16 v[48:51], v[98:101], v[192:195], v[48:51]
	v_mfma_f32_16x16x32_bf16 v[28:31], v[68:71], v[200:203], v[28:31]
	v_mfma_f32_16x16x32_bf16 v[24:27], v[98:101], v[200:203], v[24:27]
	s_barrier
	s_setprio 0
	v_add_u32_e32 v96, 0x18000, v225
	ds_read_b128 v[80:83], v96 offset:2048
	ds_read_b128 v[98:101], v96 offset:3072
	s_add_u32 s84, s84, s57
	s_addc_u32 s85, s85, 0
	s_add_i32 s29, s96, s18
	v_lshl_add_u64 v[218:219], s[84:85], 0, v[182:183]
	s_mov_b32 m0, s29
	v_lshl_add_u64 v[220:221], s[84:85], 0, v[186:187]
	global_load_lds_dwordx4 v182, s[84:85]
	s_add_i32 m0, s29, 0x2000
	s_nop 0
	global_load_lds_dwordx4 v186, s[84:85]
	s_waitcnt vmcnt(6)
	s_setprio 1
	s_barrier
	v_mfma_f32_16x16x32_bf16 v[44:47], v[228:231], v[160:163], 0
	v_mfma_f32_16x16x32_bf16 v[40:43], v[236:239], v[160:163], 0
	v_mfma_f32_16x16x32_bf16 v[20:23], v[228:231], v[196:199], 0
	s_add_i32 s29, 0, 0x18000
	v_mfma_f32_16x16x32_bf16 v[16:19], v[236:239], v[196:199], 0
	v_add_u32_e32 v96, s29, v225
	v_mfma_f32_16x16x32_bf16 v[56:59], v[228:231], v[144:147], 0
	v_mfma_f32_16x16x32_bf16 v[68:71], v[236:239], v[144:147], 0
	v_mfma_f32_16x16x32_bf16 v[44:47], v[232:235], v[192:195], v[44:47]
	v_mfma_f32_16x16x32_bf16 v[40:43], v[240:243], v[192:195], v[40:43]
	v_mfma_f32_16x16x32_bf16 v[20:23], v[232:235], v[200:203], v[20:23]
	v_mfma_f32_16x16x32_bf16 v[16:19], v[240:243], v[200:203], v[16:19]
	v_mfma_f32_16x16x32_bf16 v[56:59], v[232:235], v[148:151], v[56:59]
	v_mfma_f32_16x16x32_bf16 v[68:71], v[240:243], v[148:151], v[68:71]
	s_barrier
	s_setprio 0
	ds_read_b128 v[72:75], v96
	ds_read_b128 v[76:79], v96 offset:1024
	s_add_u32 s46, s46, s64
	s_addc_u32 s47, s47, 0
	s_mov_b32 m0, s4
	ds_read_b128 v[144:147], v227 offset:32768
	ds_read_b128 v[148:151], v227 offset:33792
	ds_read_b128 v[192:195], v227 offset:34816
	ds_read_b128 v[196:199], v227 offset:35840
	ds_read_b128 v[200:203], v227 offset:36864
	ds_read_b128 v[228:231], v227 offset:37888
	global_load_lds_dwordx4 v176, s[46:47]
	s_mov_b32 m0, s5
	s_mov_b64 exec, s[98:99]
	global_load_lds_dwordx4 v184, s[46:47]
	s_mov_b64 exec, -1
	s_waitcnt lgkmcnt(6)
	s_setprio 1
	s_barrier
	s_waitcnt lgkmcnt(0)
	v_mfma_f32_16x16x32_bf16 v[160:163], v[72:75], v[144:147], v[172:175]
	v_mfma_f32_16x16x32_bf16 v[172:175], v[76:79], v[148:151], v[160:163]
	v_mfma_f32_16x16x32_bf16 v[160:163], v[80:83], v[144:147], v[168:171]
	v_mfma_f32_16x16x32_bf16 v[156:159], v[72:75], v[192:195], v[156:159]
	v_mfma_f32_16x16x32_bf16 v[152:155], v[80:83], v[192:195], v[152:155]
	v_mfma_f32_16x16x32_bf16 v[132:135], v[72:75], v[200:203], v[132:135]
	v_mfma_f32_16x16x32_bf16 v[128:131], v[80:83], v[200:203], v[128:131]
	v_mfma_f32_16x16x32_bf16 v[168:171], v[98:101], v[148:151], v[160:163]
	v_mfma_f32_16x16x32_bf16 v[156:159], v[76:79], v[196:199], v[156:159]
	v_mfma_f32_16x16x32_bf16 v[152:155], v[98:101], v[196:199], v[152:155]
	v_mfma_f32_16x16x32_bf16 v[132:135], v[76:79], v[228:231], v[132:135]
	v_mfma_f32_16x16x32_bf16 v[128:131], v[98:101], v[228:231], v[128:131]
	s_barrier
	s_setprio 0
	s_add_i32 s46, 0, 0x1c000
	s_add_i32 s29, s29, s18
	v_add_u32_e32 v96, s46, v225
	v_lshl_add_u64 v[106:107], v[106:107], 0, s[6:7]
	s_mov_b32 m0, s29
	ds_read_b128 v[232:235], v96
	ds_read_b128 v[236:239], v96 offset:1024
	ds_read_b128 v[240:243], v96 offset:2048
	ds_read_b128 v[244:247], v96 offset:3072
	global_load_lds_dwordx4 v[106:107], off
	v_lshl_add_u64 v[106:107], v[248:249], 0, s[6:7]
	s_add_i32 m0, s29, 0x2000
	s_nop 0
	global_load_lds_dwordx4 v[106:107], off
	s_setprio 1
	s_barrier
	s_waitcnt lgkmcnt(0)
	v_mfma_f32_16x16x32_bf16 v[160:163], v[232:235], v[144:147], v[164:167]
	v_mfma_f32_16x16x32_bf16 v[102:105], v[240:243], v[144:147], v[102:105]
	v_mfma_f32_16x16x32_bf16 v[164:167], v[236:239], v[148:151], v[160:163]
	s_mov_b32 m0, s88
	v_mfma_f32_16x16x32_bf16 v[160:163], v[244:247], v[148:151], v[102:105]
	v_lshl_add_u64 v[106:107], v[250:251], 0, s[6:7]
	v_mfma_f32_16x16x32_bf16 v[102:105], v[232:235], v[192:195], v[112:115]
	v_mfma_f32_16x16x32_bf16 v[148:151], v[236:239], v[196:199], v[102:105]
	v_mfma_f32_16x16x32_bf16 v[102:105], v[240:243], v[192:195], v[124:127]
	v_mfma_f32_16x16x32_bf16 v[144:147], v[244:247], v[196:199], v[102:105]
	v_mfma_f32_16x16x32_bf16 v[102:105], v[232:235], v[200:203], v[120:123]
	v_mfma_f32_16x16x32_bf16 v[120:123], v[236:239], v[228:231], v[102:105]
	v_mfma_f32_16x16x32_bf16 v[102:105], v[240:243], v[200:203], v[116:119]
	v_mfma_f32_16x16x32_bf16 v[116:119], v[244:247], v[228:231], v[102:105]
	s_barrier
	s_setprio 0
	s_nop 2
	ds_read_b128 v[102:105], v227 offset:49152
	ds_read_b128 v[112:115], v227 offset:50176
	ds_read_b128 v[124:127], v227 offset:51200
	ds_read_b128 v[192:195], v227 offset:52224
	ds_read_b128 v[196:199], v227 offset:53248
	ds_read_b128 v[200:203], v227 offset:54272
	global_load_lds_dwordx4 v[106:107], off
	v_lshl_add_u64 v[106:107], v[252:253], 0, s[6:7]
	s_mov_b32 m0, s89
	s_mov_b64 exec, s[98:99]
	global_load_lds_dwordx4 v[106:107], off
	s_mov_b64 exec, -1
	s_waitcnt vmcnt(10)
	s_setprio 1
	s_barrier
	s_waitcnt lgkmcnt(0)
	v_mfma_f32_16x16x32_bf16 v[88:91], v[72:75], v[102:105], v[88:91]
	v_mfma_f32_16x16x32_bf16 v[84:87], v[80:83], v[102:105], v[84:87]
	v_mfma_f32_16x16x32_bf16 v[52:55], v[72:75], v[124:127], v[52:55]
	v_mfma_f32_16x16x32_bf16 v[48:51], v[80:83], v[124:127], v[48:51]
	v_mfma_f32_16x16x32_bf16 v[28:31], v[72:75], v[196:199], v[28:31]
	v_mfma_f32_16x16x32_bf16 v[24:27], v[80:83], v[196:199], v[24:27]
	v_mfma_f32_16x16x32_bf16 v[88:91], v[76:79], v[112:115], v[88:91]
	v_mfma_f32_16x16x32_bf16 v[84:87], v[98:101], v[112:115], v[84:87]
	v_mfma_f32_16x16x32_bf16 v[52:55], v[76:79], v[192:195], v[52:55]
	v_mfma_f32_16x16x32_bf16 v[48:51], v[98:101], v[192:195], v[48:51]
	v_mfma_f32_16x16x32_bf16 v[28:31], v[76:79], v[200:203], v[28:31]
	v_mfma_f32_16x16x32_bf16 v[24:27], v[98:101], v[200:203], v[24:27]
	s_barrier
	s_setprio 0
	v_add_u32_e32 v96, 0x10000, v225
	ds_read_b128 v[80:83], v96 offset:2048
	ds_read_b128 v[98:101], v96 offset:3072
	s_add_i32 s29, s46, s18
	v_lshl_add_u64 v[72:73], v[218:219], 0, s[6:7]
	s_mov_b32 m0, s29
	s_nop 0
	global_load_lds_dwordx4 v[72:73], off
	v_lshl_add_u64 v[72:73], v[220:221], 0, s[6:7]
	s_add_i32 m0, s29, 0x2000
	s_nop 0
	global_load_lds_dwordx4 v[72:73], off
	s_waitcnt vmcnt(6)
	s_setprio 1
	s_barrier
	v_mfma_f32_16x16x32_bf16 v[56:59], v[232:235], v[102:105], v[56:59]
	v_mfma_f32_16x16x32_bf16 v[76:79], v[236:239], v[112:115], v[56:59]
	v_mfma_f32_16x16x32_bf16 v[56:59], v[240:243], v[102:105], v[68:71]
	s_add_u32 s44, s44, 0x100
	v_mfma_f32_16x16x32_bf16 v[44:47], v[232:235], v[124:127], v[44:47]
	s_addc_u32 s45, s45, 0
	v_mfma_f32_16x16x32_bf16 v[40:43], v[240:243], v[124:127], v[40:43]
	s_add_u32 s87, s87, 0x100
	v_mfma_f32_16x16x32_bf16 v[20:23], v[232:235], v[196:199], v[20:23]
	s_addc_u32 vcc_lo, vcc_lo, 0
	v_mfma_f32_16x16x32_bf16 v[16:19], v[240:243], v[196:199], v[16:19]
	s_cmp_ge_u32 vcc_hi, s37
	v_mfma_f32_16x16x32_bf16 v[72:75], v[244:247], v[112:115], v[56:59]
	s_mov_b32 s46, vcc_hi
	v_mfma_f32_16x16x32_bf16 v[44:47], v[236:239], v[192:195], v[44:47]
	v_mfma_f32_16x16x32_bf16 v[40:43], v[244:247], v[192:195], v[40:43]
	v_mfma_f32_16x16x32_bf16 v[20:23], v[236:239], v[200:203], v[20:23]
	v_mfma_f32_16x16x32_bf16 v[16:19], v[244:247], v[200:203], v[16:19]
	s_barrier
	s_setprio 0
